# P8 processes each XCD's most recently written U row group first (M-group order swapped) so its A tiles come from the memory-side cache
# speedup vs baseline: 1.0142x; 1.0142x over previous
; #define PG8_WAIT_V(n) asm volatile("s_waitcnt vmcnt(" #n ")" ::: "memory")
; #define PG8_BAR __builtin_amdgcn_s_barrier()
;     __device__ bool next(int i, Unit& u) const {
;         const long L = (long)i * G + c; if (L >= nwg) return false;
;         int wgid = (int)L; { const int q = nwg / NXCD, r = nwg % NXCD, xcd = wgid % NXCD, off = wgid / NXCD; wgid = (xcd < r ? xcd * (q + 1) : r * (q + 1) + (xcd - r) * q) + off; }
;         const int nig = WG * nN, gid = wgid / nig, fm = gid * WG, gsz = (nM - fm) < WG ? (nM - fm) : WG;
;         u.pm = fm + ((wgid % nig) % gsz); u.pn = (wgid % nig) / gsz; return true;
; template <class Epi, class Sched, bool ALIGN_EPI = false, bool SP2 = false>
; __device__ __forceinline__ void gemm_phase(PG8_LAS unsigned char* lds, const Gemm g, const Sched& S, const Epi& E) {
;     ...
;     const int tid = tid_, wid = __builtin_amdgcn_readfirstlane(tid >> 6), lane = tid & 63, wr = wid >> 2, wc = wid & 3, fr = lane & 15, fq = lane >> 4;
;     const int K = g.K, nt = K / BK;
;     unsigned voffA[2], voffB[2];
; #pragma unroll
;     for (int i = 0; i < 2; ++i) { int R, C; stage_rc(tid * 16 + i * 8192, R, C); const int Rb = Epi::PERM ? ((R & ~31) + perm32(R & 31)) : R;
;         voffA[i] = (unsigned)(R * K + C) * 2u; voffB[i] = (unsigned)(Rb * K + C) * 2u; }
;     const size_t kstep = (size_t)(BK * 2);
;     const size_t hstep = (size_t)HALF * K * 2;
;     const size_t tstep = 2 * hstep;
;     const unsigned ldsw = (unsigned)wid * 1024u;
;     const int aoff = lds_byte(wr * 64 + fr, fq * 8), boff = lds_byte(wc * 32 + fr, fq * 8);
;     ...
;     Unit cur, nxt; int ui = 0;
;     if (!S.next(0, cur)) return;
;     f32x4 acc[2][2][4][2];
; #pragma unroll
;     for (int a = 0; a < 2; ++a)
; #pragma unroll
;         for (int b = 0; b < 2; ++b)
; #pragma unroll
;             for (int m = 0; m < 4; ++m)
; #pragma unroll
;                 for (int n = 0; n < 2; ++n) acc[a][b][m][n] = (f32x4){0.f, 0.f, 0.f, 0.f};
;     bf16x8 At[4][2], B0[2][2], B1[2][2];
;     const char* cA = (const char*)g.A + (size_t)cur.pm * tstep; const char* cB = (const char*)g.Bt + (size_t)cur.pn * tstep;
;     S.a_ready(cur);
;     if constexpr (SP2) {
;         PG8_STAGE(PG8_SB(0, 0), cB, voffB); PG8_STAGE(PG8_SB(0, 1), cB + hstep, voffB); PG8_STAGE(PG8_SA(0, 0), cA, voffA); PG8_STAGE(PG8_SA(0, 1), cA + hstep, voffA);
;         if (wr == 1) PG8_BAR;
;         PG8_WAIT_V(2); PG8_BAR;
.LBB0_1059:
	v_ashrrev_i32_e32 v1, 31, v186
	v_lshrrev_b32_e32 v1, 26, v1
	v_add_u32_e32 v1, v186, v1
	v_ashrrev_i32_e32 v8, 6, v1
	v_bfe_i32 v1, v186, 27, 1
	v_lshlrev_b32_e32 v0, 4, v186
	v_lshrrev_b32_e32 v1, 22, v1
	v_add_u32_e32 v1, v0, v1
	v_and_b32_e32 v1, 0xfffffc00, v1
	v_sub_u32_e32 v1, v0, v1
	v_lshrrev_b32_e32 v2, 4, v1
	v_bitop3_b32 v1, v2, v1, 32 bitop3:0x6c
	v_ashrrev_i32_e32 v3, 31, v1
	v_lshrrev_b32_e32 v3, 26, v3
	v_add_u32_e32 v3, v1, v3
	v_ashrrev_i32_e32 v9, 6, v3
	v_and_b32_e32 v3, 0xc0, v3
	v_sub_u32_e32 v1, v1, v3
	v_mov_b32_e32 v3, 1
	v_lshlrev_b32_e32 v2, 3, v8
	v_lshlrev_b32_e32 v4, 5, v8
	v_ashrrev_i16_sdwa v1, v3, sext(v1) dst_sel:DWORD dst_unused:UNUSED_PAD src0_sel:DWORD src1_sel:BYTE_0
	s_add_i32 s0, s2, s0
	v_and_b32_e32 v2, 0x3fff0, v2
	v_and_b32_e32 v4, 32, v4
	v_bfe_i32 v10, v1, 0, 16
	s_ashr_i32 s2, s0, 31
	v_add_u32_e32 v1, v4, v10
	v_add_lshl_u32 v2, v9, v2, 14
	v_add_u32_e32 v0, 0x2000, v0
	s_lshr_b32 s2, s2, 27
	v_lshl_add_u32 v144, v1, 1, v2
	v_ashrrev_i32_e32 v1, 31, v0
	s_add_i32 s2, s0, s2
	v_lshrrev_b32_e32 v1, 22, v1
	s_ashr_i32 s3, s2, 5
	s_and_b32 s2, s2, 0xffe0
	v_add_u32_e32 v1, v0, v1
	s_sub_i32 s2, s0, s2
	v_ashrrev_i32_e32 v11, 10, v1
	s_bfe_i32 s0, s2, 0x80000
	v_mul_i32_i24_e32 v1, 0x400, v11
	s_bfe_u32 s0, s0, 0x2000d
	v_sub_u32_e32 v0, v0, v1
	s_add_i32 s5, s2, s0
	v_lshrrev_b32_e32 v1, 4, v0
	s_bfe_i32 s0, s5, 0x80000
	s_and_b32 s5, s5, 0xfc
	v_bitop3_b32 v0, v1, v0, 32 bitop3:0x6c
	s_sub_i32 s2, s2, s5
	v_ashrrev_i32_e32 v2, 31, v0
	s_lshl_b32 s3, s3, 2
	s_xor_b32 s3, s3, 4
	s_sext_i32_i16 s0, s0
	s_sext_i32_i8 s2, s2
	s_ashr_i32 s1, s6, 8
	v_lshrrev_b32_e32 v2, 26, v2
	s_lshr_b32 s0, s0, 2
	s_add_i32 s24, s3, s2
	v_add_u32_e32 v2, v0, v2
	s_ashr_i32 s4, s6, 6
	s_ashr_i32 s25, s24, 31
	s_bfe_i64 s[8:9], s[0:1], 0x100000
	v_ashrrev_i32_e32 v12, 6, v2
	v_and_b32_e32 v2, 0xc0, v2
	s_lshl_b32 s34, s4, 10
	s_lshl_b64 s[2:3], s[24:25], 22
	s_lshl_b64 s[8:9], s[8:9], 22
	v_readlane_b32 s10, v236, 54
	v_sub_u32_e32 v0, v0, v2
	v_readlane_b32 s11, v236, 55
	s_add_u32 s28, s10, s8
	v_lshlrev_b32_e32 v1, 3, v11
	v_lshlrev_b32_e32 v4, 5, v11
	v_ashrrev_i16_sdwa v0, v3, sext(v0) dst_sel:DWORD dst_unused:UNUSED_PAD src0_sel:DWORD src1_sel:BYTE_0
	s_addc_u32 s29, s11, s9
	s_add_i32 s35, s34, 0
	v_and_b32_e32 v1, 0x3fff0, v1
	v_and_b32_e32 v4, 32, v4
	v_bfe_i32 v13, v0, 0, 16
	s_add_i32 m0, s35, 0x10000
	v_add_u32_e32 v0, v4, v13
	v_add_lshl_u32 v1, v12, v1, 14
	global_load_lds_dwordx4 v144, s[28:29]
	s_add_i32 m0, s35, 0x12000
	v_lshl_add_u32 v146, v0, 1, v1
	s_add_u32 s8, s28, 0x200000
	global_load_lds_dwordx4 v146, s[28:29]
	s_addc_u32 s9, s29, 0
	s_add_i32 m0, s35, 0x14000
	v_mov_b32_e32 v145, 0
	global_load_lds_dwordx4 v144, s[8:9]
	s_add_i32 m0, s35, 0x16000
	s_add_u32 s26, s72, s2
	s_addc_u32 s27, s73, s3
	s_add_i32 s36, s35, 0x2000
	global_load_lds_dwordx4 v146, s[8:9]
	s_mov_b32 m0, s35
	s_add_u32 s2, s26, 0x200000
	global_load_lds_dwordx4 v144, s[26:27]
	s_mov_b32 m0, s36
	s_addc_u32 s3, s27, 0
	s_add_i32 s37, s35, 0x4000
	global_load_lds_dwordx4 v146, s[26:27]
	s_mov_b32 m0, s37
	s_add_i32 s38, s35, 0x6000
	global_load_lds_dwordx4 v144, s[2:3]
	s_mov_b32 m0, s38
	v_mov_b32_e32 v147, v145
	global_load_lds_dwordx4 v146, s[2:3]
	s_cmp_eq_u32 s1, 1
	s_mov_b32 s39, 0
	v_lshl_add_u64 v[6:7], s[28:29], 0, v[144:145]
	v_lshl_add_u64 v[4:5], s[28:29], 0, v[146:147]
	v_lshl_add_u64 v[0:1], s[26:27], 0, v[144:145]
	s_cselect_b64 s[2:3], -1, 0
	s_cmp_lg_u32 s1, 1
	v_lshl_add_u64 v[2:3], s[26:27], 0, v[146:147]
	s_cbranch_scc1 .LBB0_1061
	s_barrier

;     __device__ __forceinline__ bool next(int i, Unit& u) const { if (!base.next(i >> 1, u)) return false; if (i & 1) { u.pm += 64; u.pn += 8; } return true; }
;     __device__ bool next(int i, Unit& u) const {
;         const long L = (long)i * G + c; if (L >= nwg) return false;
;         int wgid = (int)L; { const int q = nwg / NXCD, r = nwg % NXCD, xcd = wgid % NXCD, off = wgid / NXCD; wgid = (xcd < r ? xcd * (q + 1) : r * (q + 1) + (xcd - r) * q) + off; }
;         const int nig = WG * nN, gid = wgid / nig, fm = gid * WG, gsz = (nM - fm) < WG ? (nM - fm) : WG;
;         u.pm = fm + ((wgid % nig) % gsz); u.pn = (wgid % nig) / gsz; return true;
.LBB0_1069:
	s_ashr_i32 s16, s18, 3
	s_add_i32 s16, s20, s16
	s_ashr_i32 s17, s16, 31
	s_lshr_b32 s17, s17, 27
	s_add_i32 s17, s16, s17
	s_ashr_i32 s18, s17, 5
	s_lshl_b32 s18, s18, 2
	s_xor_b32 s18, s18, 4
	s_sub_i32 s19, 64, s18
	s_min_i32 s19, s19, 4
	s_abs_i32 s20, s19
	v_cvt_f32_u32_e32 v0, s20
	s_sub_i32 s22, 0, s20
	s_andn2_b32 s17, s17, 31
	s_sub_i32 s17, s16, s17
	v_rcp_iflag_f32_e32 v0, v0
	s_abs_i32 s16, s17
	s_xor_b32 s21, s17, s19
	s_ashr_i32 s21, s21, 31
	v_mul_f32_e32 v0, 0x4f7ffffe, v0
	v_cvt_u32_f32_e32 v0, v0
	s_nop 0
	v_readfirstlane_b32 s23, v0
	s_mul_i32 s22, s22, s23
	s_mul_hi_u32 s22, s23, s22
	s_add_i32 s23, s23, s22
	s_mul_hi_u32 s22, s16, s23
	s_mul_i32 s23, s22, s20
	s_sub_i32 s16, s16, s23
	s_add_i32 s30, s22, 1
	s_sub_i32 s23, s16, s20
	s_cmp_ge_u32 s16, s20
	s_cselect_b32 s22, s30, s22
	s_cselect_b32 s16, s23, s16
	s_add_i32 s23, s22, 1
	s_cmp_ge_u32 s16, s20
	s_cselect_b32 s16, s23, s22
	s_xor_b32 s16, s16, s21
	s_sub_i32 s16, s16, s21
	s_mul_i32 s19, s16, s19
	s_sub_i32 s17, s17, s19
	s_add_i32 s18, s18, s17
